# previous plus phase 0 rebalanced: the 32 workgroups that build the S5 chunk matrices skip the input rmsnorm, the other 224 cover all rows
# baseline (speedup 1.0000x reference)
;     __device__ __forceinline__ const float* in(int i) const { return *(const __attribute__((address_space(4))) cfptr_t*)(p + 8 * i); }
; #define LAUNDER(Fx) Ctx Fx = F; asm volatile("" : "+v"(Fx.tid)); Fx.lane = Fx.tid & 63; Fx.wave = __builtin_amdgcn_readfirstlane(Fx.tid >> 6)
; template <bool OUT_F32> __device__ __forceinline__ void phase_rmsnorm(const KA& A, const Ctx& F, const float* src, const float* gain, void* dst) {
;     const int gw = F.bid * NWAVES + F.wave, NGW = F.G * NWAVES;
;     f32x4 gv[4];
; #pragma unroll
;     for (int j = 0; j < 4; ++j) gv[j] = *((const f32x4*)gain + F.lane + 64 * j);
; #pragma unroll 1
;     for (int m0 = gw; m0 < T; m0 += 4 * NGW) {
; __device__ __forceinline__ void run_phase(const KA& A, const Ctx& F, int ph) {
;     ...
;     if (k == 20) { { LAUNDER(F2); for (int it = F2.bid; it < 32; it += F2.G) ssm_prep(A, F2, it >> 4, it & 15); } __syncthreads(); { LAUNDER(F1); phase_prep(A, F1); } { LAUNDER(F3); phase_rmsnorm<false>(A, F3, A.in(0), A.in(1), XN); } }
.LBB0_125:
	s_or_b64 exec, exec, s[4:5]
	v_mov_b32_e32 v0, v242
	s_movk_i32 s56, 0x90
	s_cmp_lt_u32 s80, 32
	s_cbranch_scc1 .LBB0_134
	s_add_i32 s1, s80, -32
	s_lshl_b32 s1, s1, 3
	v_readfirstlane_b32 s0, v0
	s_ashr_i32 s0, s0, 6
	s_add_i32 s10, s0, s1
	s_cmpk_gt_i32 s10, 0x7fff
	s_movk_i32 s56, 0x90
	s_cbranch_scc1 .LBB0_134
	v_readlane_b32 s4, v253, 58
	v_readlane_b32 s5, v253, 59
	s_load_dwordx4 s[0:3], s[4:5], 0x0
	v_and_b32_e32 v16, 63, v0
	v_lshlrev_b32_e32 v80, 4, v16
	s_add_i32 s12, s93, -32
	s_lshl_b32 s13, s12, 4
	s_lshl_b32 s12, s12, 3
	s_waitcnt lgkmcnt(0)
	global_load_dwordx4 v[0:3], v80, s[2:3]
	global_load_dwordx4 v[4:7], v80, s[2:3] offset:1024
	global_load_dwordx4 v[8:11], v80, s[2:3] offset:2048
	global_load_dwordx4 v[12:15], v80, s[2:3] offset:3072
	v_lshl_add_u64 v[64:65], s[0:1], 0, v[80:81]
	v_lshlrev_b32_e32 v80, 3, v16
	v_lshl_add_u64 v[66:67], s[28:29], 0, v[80:81]
	s_branch .LBB0_128

; __device__ __forceinline__ unsigned pk2(float lo, float hi) { return cvtpk(lo, hi); }
; __device__ __forceinline__ float wave_sum(float v) { v += dppf<0xB1>(v); v += dppf<0x4E>(v); v += dppf<0x141>(v); v += dppf<0x140>(v); v += shx<16>(v); return xsum32(v); }
; template <bool OUT_F32> __device__ __forceinline__ void phase_rmsnorm(const KA& A, const Ctx& F, const float* src, const float* gain, void* dst) {
;     ...
;     for (int m0 = gw; m0 < T; m0 += 4 * NGW) {
;         f32x4 v[4][4]; float s[4];
; #pragma unroll
;         for (int q = 0; q < 4; ++q) { const int m = (m0 + q * NGW < T) ? m0 + q * NGW : m0; const f32x4* xr = (const f32x4*)(src + (size_t)m * D) + F.lane;
; #pragma unroll
;             for (int j = 0; j < 4; ++j) v[q][j] = xr[64 * j]; }
; #pragma unroll
;         for (int q = 0; q < 4; ++q) { s[q] = 0.f;
; #pragma unroll
;             for (int j = 0; j < 4; ++j) s[q] += (v[q][j].x * v[q][j].x + v[q][j].y * v[q][j].y) + (v[q][j].z * v[q][j].z + v[q][j].w * v[q][j].w); }
; #pragma unroll
;         for (int q = 0; q < 4; ++q) { const int m = m0 + q * NGW; if (m < T) {
;             const float rs = __builtin_amdgcn_rsqf(wave_sum(s[q]) * (1.0f / D) + NORM_EPS);
;             if (OUT_F32) {
;                 f32x4* o = (f32x4*)((float*)dst + (size_t)m * D) + F.lane;
; #pragma unroll
;                 for (int j = 0; j < 4; ++j) o[64 * j] = v[q][j] * rs * gv[j];
;             } else {
;                 v2u* o = (v2u*)((bf16*)dst + (size_t)m * D) + F.lane;
; #pragma unroll
;                 for (int j = 0; j < 4; ++j) { const f32x4 y = v[q][j] * rs * gv[j]; v2u w; w.x = pk2(y.x, y.y); w.y = pk2(y.z, y.w); o[64 * j] = w; }
;             } }
.LBB0_128:
	s_add_i32 s0, s10, s12
	s_cmp_lt_i32 s0, 0x8000
	s_cselect_b32 s2, s0, s10
	s_ashr_i32 s3, s2, 31
	s_lshl_b64 s[14:15], s[2:3], 12
	s_add_i32 s6, s13, s10
	s_cmp_lt_i32 s6, 0x8000
	s_cselect_b64 s[8:9], -1, 0
	s_and_b64 s[2:3], s[8:9], exec
	s_cselect_b32 s2, s6, s10
	s_ashr_i32 s3, s2, 31
	s_mul_i32 s1, s12, 3
	s_lshl_b64 s[16:17], s[2:3], 12
	s_add_i32 s2, s1, s10
	s_cmp_lt_i32 s2, 0x8000
	s_cselect_b64 s[4:5], -1, 0
	s_and_b64 s[18:19], s[4:5], exec
	s_cselect_b32 s18, s2, s10
	s_ashr_i32 s11, s10, 31
	s_lshl_b64 s[20:21], s[10:11], 12
	s_waitcnt vmcnt(4)
	v_lshl_add_u64 v[16:17], v[64:65], 0, s[20:21]
	global_load_dwordx4 v[68:71], v[16:17], off
	global_load_dwordx4 v[72:75], v[16:17], off offset:1024
	global_load_dwordx4 v[76:79], v[16:17], off offset:2048
	global_load_dwordx4 v[82:85], v[16:17], off offset:3072
	v_lshl_add_u64 v[16:17], v[64:65], 0, s[14:15]
	s_ashr_i32 s19, s18, 31
	global_load_dwordx4 v[60:63], v[16:17], off
	global_load_dwordx4 v[56:59], v[16:17], off offset:1024
	global_load_dwordx4 v[52:55], v[16:17], off offset:2048
	global_load_dwordx4 v[48:51], v[16:17], off offset:3072
	v_lshl_add_u64 v[16:17], v[64:65], 0, s[16:17]
	s_lshl_b64 s[14:15], s[18:19], 12
	global_load_dwordx4 v[44:47], v[16:17], off
	global_load_dwordx4 v[40:43], v[16:17], off offset:1024
	global_load_dwordx4 v[36:39], v[16:17], off offset:2048
	global_load_dwordx4 v[32:35], v[16:17], off offset:3072
	v_lshl_add_u64 v[16:17], v[64:65], 0, s[14:15]
	global_load_dwordx4 v[28:31], v[16:17], off
	global_load_dwordx4 v[24:27], v[16:17], off offset:1024
	global_load_dwordx4 v[20:23], v[16:17], off offset:2048
	s_nop 0
	global_load_dwordx4 v[16:19], v[16:17], off offset:3072
	s_lshl_b64 s[10:11], s[10:11], 11
	s_cmpk_gt_i32 s0, 0x7fff
	s_waitcnt vmcnt(15)
	v_mul_f32_e32 v80, v69, v69
	v_mul_f32_e32 v86, v71, v71
	s_waitcnt vmcnt(14)
	v_mul_f32_e32 v87, v73, v73
	v_mul_f32_e32 v88, v75, v75
	s_waitcnt vmcnt(13)
	v_mul_f32_e32 v89, v77, v77
	v_mul_f32_e32 v90, v79, v79
	v_fmac_f32_e32 v80, v68, v68
	v_fmac_f32_e32 v86, v70, v70
	v_fmac_f32_e32 v87, v72, v72
	v_fmac_f32_e32 v88, v74, v74
	s_waitcnt vmcnt(12)
	v_mul_f32_e32 v91, v83, v83
	v_mul_f32_e32 v92, v85, v85
	v_fmac_f32_e32 v89, v76, v76
	v_fmac_f32_e32 v90, v78, v78
	v_add_f32_e32 v80, v80, v86
	v_add_f32_e32 v86, v87, v88
	v_fmac_f32_e32 v91, v82, v82
	v_fmac_f32_e32 v92, v84, v84
	v_add_f32_e32 v87, v89, v90
	v_add_f32_e32 v80, v80, v86
	v_add_f32_e32 v88, v91, v92
	v_add_f32_e32 v80, v80, v87
	v_add_f32_e32 v80, v80, v88
	s_nop 1
	v_add_f32_dpp v80, v80, v80 quad_perm:[1,0,3,2] row_mask:0xf bank_mask:0xf bound_ctrl:1
	s_nop 1
	v_add_f32_dpp v80, v80, v80 quad_perm:[2,3,0,1] row_mask:0xf bank_mask:0xf bound_ctrl:1
	s_nop 1
	v_add_f32_dpp v80, v80, v80 row_half_mirror row_mask:0xf bank_mask:0xf bound_ctrl:1
	s_nop 1
	v_add_f32_dpp v80, v80, v80 row_mirror row_mask:0xf bank_mask:0xf bound_ctrl:1
	ds_swizzle_b32 v86, v80 offset:swizzle(SWAP,16)
	s_waitcnt lgkmcnt(0)
	v_add_f32_e32 v80, v80, v86
	v_mov_b32_e32 v86, v80
	s_nop 1
	v_permlane32_swap_b32_e32 v80, v86
	v_add_f32_e32 v80, v80, v86
	v_fmamk_f32 v80, v80, 0x3a800000, v220
	v_rsq_f32_e32 v80, v80
	v_lshl_add_u64 v[86:87], v[66:67], 0, s[10:11]
	v_pk_mul_f32 v[68:69], v[68:69], v[80:81] op_sel_hi:[1,0]
	v_pk_mul_f32 v[70:71], v[70:71], v[80:81] op_sel_hi:[1,0]
	v_pk_mul_f32 v[72:73], v[72:73], v[80:81] op_sel_hi:[1,0]
	v_pk_mul_f32 v[74:75], v[74:75], v[80:81] op_sel_hi:[1,0]
	v_pk_mul_f32 v[76:77], v[76:77], v[80:81] op_sel_hi:[1,0]
	v_pk_mul_f32 v[78:79], v[78:79], v[80:81] op_sel_hi:[1,0]
	v_pk_mul_f32 v[82:83], v[82:83], v[80:81] op_sel_hi:[1,0]
	v_pk_mul_f32 v[84:85], v[84:85], v[80:81] op_sel_hi:[1,0]
	v_pk_mul_f32 v[70:71], v[2:3], v[70:71]
	v_pk_mul_f32 v[68:69], v[0:1], v[68:69]
	v_pk_mul_f32 v[74:75], v[6:7], v[74:75]
	v_pk_mul_f32 v[72:73], v[4:5], v[72:73]
	v_pk_mul_f32 v[78:79], v[10:11], v[78:79]
	v_pk_mul_f32 v[76:77], v[8:9], v[76:77]
	v_pk_mul_f32 v[84:85], v[14:15], v[84:85]
	v_pk_mul_f32 v[82:83], v[12:13], v[82:83]
	v_cvt_pk_bf16_f32 v68, v68, v69
	v_cvt_pk_bf16_f32 v69, v70, v71
	v_cvt_pk_bf16_f32 v70, v72, v73
	v_cvt_pk_bf16_f32 v71, v74, v75
	v_cvt_pk_bf16_f32 v72, v76, v77
	v_cvt_pk_bf16_f32 v73, v78, v79
	v_cvt_pk_bf16_f32 v74, v82, v83
	v_cvt_pk_bf16_f32 v75, v84, v85
	global_store_dwordx2 v[86:87], v[68:69], off
	global_store_dwordx2 v[86:87], v[70:71], off offset:512
	global_store_dwordx2 v[86:87], v[72:73], off offset:1024
	global_store_dwordx2 v[86:87], v[74:75], off offset:1536
	s_cbranch_scc0 .LBB0_131
	s_andn2_b64 vcc, exec, s[8:9]
	s_cbranch_vccz .LBB0_132
